# in-projection weight conversion tiles (state and gate parts): 16 row loads in flight instead of serialized groups
# speedup vs baseline: 1.0114x; 1.0114x over previous
; DI int tidx() { int t = __builtin_amdgcn_workitem_id_x(); asm volatile("" : "+v"(t)); return t; }
; DI float wsrc(KP p, int job, int l, int k, int n) {
;     ...
;       return p->w_in[((size_t)l * 1024 + k) * INW + c];
;     }
;     case J_WING: return p->w_in[((size_t)l * 1024 + k) * INW + 3232 + n];
; DI void conv_tile(KP p, u16* dst, int K, int job, int l, int nt, int kt, char* smem) {
;   float* tile = (float*)smem;
;   const int tid = tidx();
;   __syncthreads();
;   {
;     const int n = nt * 64 + (tid & 63), kb = kt * 64 + (tid >> 6) * 16;
; #pragma unroll
;     for (int i = 0; i < 16; ++i) tile[((tid >> 6) * 16 + i) * 65 + (tid & 63)] = wsrc(p, job, l, kb + i, n);
;   }
;   __syncthreads();
.LBB0_232:
	s_andn2_b64 vcc, exec, s[8:9]
	s_cbranch_vccnz .LBB0_234
	v_mov_b32_e32 v16, v0
	s_barrier
	s_lshl_b32 s2, s35, 2
	s_load_dwordx2 s[4:5], s[24:25], 0x40
	s_and_b32 s3, s2, 0x1fc0
	s_lshl_b32 s2, s35, 6
	v_ashrrev_i32_e32 v3, 2, v16
	s_and_b32 s2, s2, 0x3c0
	v_and_b32_e32 v12, -16, v3
	v_add_u32_e32 v4, s2, v12
	v_ashrrev_i32_e32 v5, 31, v4
	s_addk_i32 s3, 0xf300
	v_and_b32_e32 v2, 63, v16
	v_lshl_add_u64 v[8:9], v[4:5], 0, s[74:75]
	s_waitcnt lgkmcnt(0)
	v_mov_b64_e32 v[6:7], s[4:5]
	s_movk_i32 s8, 0x6280
	v_or_b32_e32 v198, s3, v2
	v_mad_u64_u32 v[10:11], s[4:5], v8, s8, v[6:7]
	v_mad_i32_i24 v11, v9, s8, v11
	v_lshlrev_b64 v[8:9], 2, v[198:199]
	v_lshl_add_u64 v[10:11], v[10:11], 0, v[8:9]
	v_add_co_u32_e32 v10, vcc, s38, v10
	v_lshlrev_b32_e32 v2, 2, v2
	s_nop 0
	v_addc_co_u32_e32 v11, vcc, 0, v11, vcc
	s_mov_b64 vcc, 0x6280
	v_mov_b32_e32 v34, v10
	v_mov_b32_e32 v35, v11
	global_load_dword v36, v[34:35], off offset:640
	v_lshl_add_u64 v[34:35], v[34:35], 0, vcc
	global_load_dword v37, v[34:35], off offset:640
	v_lshl_add_u64 v[34:35], v[34:35], 0, vcc
	global_load_dword v38, v[34:35], off offset:640
	v_lshl_add_u64 v[34:35], v[34:35], 0, vcc
	global_load_dword v39, v[34:35], off offset:640
	v_lshl_add_u64 v[34:35], v[34:35], 0, vcc
	global_load_dword v40, v[34:35], off offset:640
	v_lshl_add_u64 v[34:35], v[34:35], 0, vcc
	global_load_dword v41, v[34:35], off offset:640
	v_lshl_add_u64 v[34:35], v[34:35], 0, vcc
	global_load_dword v42, v[34:35], off offset:640
	v_lshl_add_u64 v[34:35], v[34:35], 0, vcc
	global_load_dword v43, v[34:35], off offset:640
	v_lshl_add_u64 v[34:35], v[34:35], 0, vcc
	global_load_dword v44, v[34:35], off offset:640
	v_lshl_add_u64 v[34:35], v[34:35], 0, vcc
	global_load_dword v45, v[34:35], off offset:640
	v_lshl_add_u64 v[34:35], v[34:35], 0, vcc
	global_load_dword v46, v[34:35], off offset:640
	v_lshl_add_u64 v[34:35], v[34:35], 0, vcc
	global_load_dword v47, v[34:35], off offset:640
	v_lshl_add_u64 v[34:35], v[34:35], 0, vcc
	global_load_dword v48, v[34:35], off offset:640
	v_lshl_add_u64 v[34:35], v[34:35], 0, vcc
	global_load_dword v49, v[34:35], off offset:640
	v_lshl_add_u64 v[34:35], v[34:35], 0, vcc
	global_load_dword v50, v[34:35], off offset:640
	v_lshl_add_u64 v[34:35], v[34:35], 0, vcc
	global_load_dword v51, v[34:35], off offset:640
	v_mad_u64_u32 v[10:11], s[4:5], v12, s54, v[2:3]
	s_lshl_b32 s40, s2, 1
	s_waitcnt vmcnt(0)
	ds_write_b32 v10, v36
	ds_write_b32 v10, v37 offset:260
	ds_write_b32 v10, v38 offset:520
	ds_write_b32 v10, v39 offset:780
	ds_write_b32 v10, v40 offset:1040
	ds_write_b32 v10, v41 offset:1300
	ds_write_b32 v10, v42 offset:1560
	ds_write_b32 v10, v43 offset:1820
	ds_write_b32 v10, v44 offset:2080
	ds_write_b32 v10, v45 offset:2340
	ds_write_b32 v10, v46 offset:2600
	ds_write_b32 v10, v47 offset:2860
	ds_write_b32 v10, v48 offset:3120
	ds_write_b32 v10, v49 offset:3380
	ds_write_b32 v10, v50 offset:3640
	ds_write_b32 v10, v51 offset:3900
	v_lshlrev_b32_e32 v2, 4, v16
	v_and_b32_e32 v14, 48, v2
	v_and_b32_e32 v2, -4, v16
	v_lshlrev_b32_e32 v198, 1, v14
	v_mul_u32_u24_e32 v4, 0x41, v14
	v_lshl_add_u32 v2, v4, 2, v2
	s_waitcnt lgkmcnt(0)
	s_barrier
	ds_read2_b32 v[4:5], v2 offset1:65
	ds_read2_b32 v[6:7], v2 offset0:130 offset1:195
	v_add_u32_e32 v8, 0x400, v2
	v_add_u32_e32 v10, 0x800, v2
	v_add_u32_e32 v2, 0xc00, v2
	s_waitcnt lgkmcnt(1)
	v_cvt_pk_bf16_f32 v4, v4, v5
	s_waitcnt lgkmcnt(0)
	v_cvt_pk_bf16_f32 v5, v6, v7
	ds_read2_b32 v[6:7], v8 offset0:4 offset1:69
	ds_read2_b32 v[8:9], v8 offset0:134 offset1:199
	ds_read2_b32 v[12:13], v2 offset0:142 offset1:207
	s_waitcnt lgkmcnt(2)
	v_cvt_pk_bf16_f32 v6, v6, v7
	s_waitcnt lgkmcnt(1)
	v_cvt_pk_bf16_f32 v7, v8, v9
	ds_read2_b32 v[8:9], v10 offset0:8 offset1:73
	ds_read2_b32 v[10:11], v10 offset0:138 offset1:203
	s_waitcnt lgkmcnt(1)
	v_cvt_pk_bf16_f32 v8, v8, v9
	s_waitcnt lgkmcnt(0)
	v_cvt_pk_bf16_f32 v9, v10, v11
	ds_read2_b32 v[10:11], v2 offset0:12 offset1:77
	v_add_u32_e32 v2, s3, v3
	v_ashrrev_i32_e32 v3, 31, v2
	v_lshlrev_b64 v[2:3], 11, v[2:3]
	v_lshl_add_u64 v[2:3], s[26:27], 0, v[2:3]
	v_lshl_add_u64 v[2:3], v[2:3], 0, s[40:41]
	v_lshl_add_u64 v[2:3], v[2:3], 0, v[198:199]
	s_mov_b64 s[2:3], 0xd7d0000
	s_waitcnt lgkmcnt(0)
	v_cvt_pk_bf16_f32 v10, v10, v11
	v_cvt_pk_bf16_f32 v11, v12, v13
	v_lshl_add_u64 v[12:13], v[2:3], 0, s[2:3]
	v_add_co_u32_e32 v2, vcc, 0xd7d0000, v2
	s_nop 1
	v_addc_co_u32_e32 v3, vcc, 0, v3, vcc
	global_store_dwordx4 v[2:3], v[4:7], off
	global_store_dwordx4 v[12:13], v[8:11], off offset:16

; DI int tidx() { int t = __builtin_amdgcn_workitem_id_x(); asm volatile("" : "+v"(t)); return t; }
; DI unsigned pack2(float lo, float hi) { f32x2 v; v.x = lo; v.y = hi; return __builtin_bit_cast(unsigned, __builtin_convertvector(v, hwbf2)); }
; DI float wsrc(KP p, int job, int l, int k, int n) {
;     ...
;     case J_WINS: {
;       int c;
;       if (n < 672) c = n; else if (n < 768) return 0.f; else c = n - 96;
;       return p->w_in[((size_t)l * 1024 + k) * INW + c];
;     }
; DI void conv_tile(KP p, u16* dst, int K, int job, int l, int nt, int kt, char* smem) {
;   float* tile = (float*)smem;
;   const int tid = tidx();
;   __syncthreads();
;   {
;     const int n = nt * 64 + (tid & 63), kb = kt * 64 + (tid >> 6) * 16;
; #pragma unroll
;     for (int i = 0; i < 16; ++i) tile[((tid >> 6) * 16 + i) * 65 + (tid & 63)] = wsrc(p, job, l, kb + i, n);
;   }
;   __syncthreads();
;   {
;     const int nl = tid >> 2, kq = (tid & 3) * 16;
;     unsigned v[8];
; #pragma unroll
;     for (int j = 0; j < 8; ++j) v[j] = pack2(tile[(kq + 2 * j) * 65 + nl], tile[(kq + 2 * j + 1) * 65 + nl]);
;     u16* d = dst + (size_t)(nt * 64 + nl) * K + kt * 64 + kq;
;     *(u32x4*)d = u32x4{v[0], v[1], v[2], v[3]};
;     *(u32x4*)(d + 8) = u32x4{v[4], v[5], v[6], v[7]};
;   }
.LBB0_235:
	s_andn2_b64 vcc, exec, s[8:9]
	s_cbranch_vccnz .LBB0_248
	s_lshl_b32 s2, s35, 2
	v_mov_b32_e32 v6, v0
	s_and_b32 s3, s2, 0xfc0
	s_lshl_b32 s2, s35, 6
	s_and_b32 s2, s2, 0x3c0
	v_and_b32_e32 v4, 63, v6
	v_or_b32_e32 v3, s3, v4
	v_ashrrev_i32_e32 v5, 2, v6
	s_cmpk_gt_u32 s3, 0x2ff
	v_and_b32_e32 v7, -16, v5
	v_cmp_gt_u32_e32 vcc, s39, v3
	s_cselect_b64 s[4:5], -1, 0
	v_add_u32_e32 v9, 0xffffffa0, v3
	v_add_u32_e32 v2, s2, v7
	s_or_b64 s[8:9], s[4:5], vcc
	v_mov_b32_e32 v8, 0
	v_cndmask_b32_e32 v198, v9, v3, vcc
	s_barrier
	v_lshlrev_b32_e32 v4, 2, v4
	v_mul_lo_u32 v3, v7, s54
	v_add_u32_e32 v3, v4, v3
	v_mov_b32_e32 v36, 0
	v_mov_b32_e32 v37, 0
	v_mov_b32_e32 v38, 0
	v_mov_b32_e32 v39, 0
	v_mov_b32_e32 v40, 0
	v_mov_b32_e32 v41, 0
	v_mov_b32_e32 v42, 0
	v_mov_b32_e32 v43, 0
	v_mov_b32_e32 v44, 0
	v_mov_b32_e32 v45, 0
	v_mov_b32_e32 v46, 0
	v_mov_b32_e32 v47, 0
	v_mov_b32_e32 v48, 0
	v_mov_b32_e32 v49, 0
	v_mov_b32_e32 v50, 0
	v_mov_b32_e32 v51, 0
	s_load_dwordx2 s[4:5], s[24:25], 0x40
	v_mov_b32_e32 v52, v2
	v_ashrrev_i32_e32 v53, 31, v2
	v_lshl_add_u64 v[52:53], v[52:53], 0, s[74:75]
	s_movk_i32 s22, 0x6280
	s_waitcnt lgkmcnt(0)
	v_mov_b64_e32 v[34:35], s[4:5]
	v_mad_u64_u32 v[34:35], s[4:5], v52, s22, v[34:35]
	v_mad_i32_i24 v35, v53, s22, v35
	v_lshl_add_u64 v[34:35], v[198:199], 2, v[34:35]
	s_mov_b64 vcc, 0x6280
	s_and_saveexec_b64 s[10:11], s[8:9]
	global_load_dword v36, v[34:35], off
	v_lshl_add_u64 v[34:35], v[34:35], 0, vcc
	global_load_dword v37, v[34:35], off
	v_lshl_add_u64 v[34:35], v[34:35], 0, vcc
	global_load_dword v38, v[34:35], off
	v_lshl_add_u64 v[34:35], v[34:35], 0, vcc
	global_load_dword v39, v[34:35], off
	v_lshl_add_u64 v[34:35], v[34:35], 0, vcc
	global_load_dword v40, v[34:35], off
	v_lshl_add_u64 v[34:35], v[34:35], 0, vcc
	global_load_dword v41, v[34:35], off
	v_lshl_add_u64 v[34:35], v[34:35], 0, vcc
	global_load_dword v42, v[34:35], off
	v_lshl_add_u64 v[34:35], v[34:35], 0, vcc
	global_load_dword v43, v[34:35], off
	v_lshl_add_u64 v[34:35], v[34:35], 0, vcc
	global_load_dword v44, v[34:35], off
	v_lshl_add_u64 v[34:35], v[34:35], 0, vcc
	global_load_dword v45, v[34:35], off
	v_lshl_add_u64 v[34:35], v[34:35], 0, vcc
	global_load_dword v46, v[34:35], off
	v_lshl_add_u64 v[34:35], v[34:35], 0, vcc
	global_load_dword v47, v[34:35], off
	v_lshl_add_u64 v[34:35], v[34:35], 0, vcc
	global_load_dword v48, v[34:35], off
	v_lshl_add_u64 v[34:35], v[34:35], 0, vcc
	global_load_dword v49, v[34:35], off
	v_lshl_add_u64 v[34:35], v[34:35], 0, vcc
	global_load_dword v50, v[34:35], off
	v_lshl_add_u64 v[34:35], v[34:35], 0, vcc
	global_load_dword v51, v[34:35], off
	s_or_b64 exec, exec, s[10:11]
	s_waitcnt vmcnt(0)
	ds_write_b32 v3, v36
	ds_write_b32 v3, v37 offset:260
	ds_write_b32 v3, v38 offset:520
	ds_write_b32 v3, v39 offset:780
	ds_write_b32 v3, v40 offset:1040
	ds_write_b32 v3, v41 offset:1300
	ds_write_b32 v3, v42 offset:1560
	ds_write_b32 v3, v43 offset:1820
	ds_write_b32 v3, v44 offset:2080
	ds_write_b32 v3, v45 offset:2340
	ds_write_b32 v3, v46 offset:2600
	ds_write_b32 v3, v47 offset:2860
	ds_write_b32 v3, v48 offset:3120
	ds_write_b32 v3, v49 offset:3380
	ds_write_b32 v3, v50 offset:3640
	ds_write_b32 v3, v51 offset:3900
	v_lshlrev_b32_e32 v2, 4, v6
	v_and_b32_e32 v4, 48, v2
	v_mul_u32_u24_e32 v2, 0x41, v4
	v_lshlrev_b32_e32 v2, 2, v2
	v_lshl_add_u32 v12, v5, 2, v2
	s_waitcnt lgkmcnt(0)
	s_barrier
	ds_read2_b32 v[2:3], v12 offset1:65
	v_add_u32_e32 v9, 0x400, v12
	v_add_u32_e32 v11, 0x800, v12
	v_add_u32_e32 v13, 0xc00, v12
	s_lshl_b32 s40, s2, 1
	s_waitcnt lgkmcnt(0)
	v_cvt_pk_bf16_f32 v6, v2, v3
	ds_read2_b32 v[2:3], v12 offset0:130 offset1:195
	v_lshlrev_b32_e32 v198, 1, v4
	s_waitcnt lgkmcnt(0)
	v_cvt_pk_bf16_f32 v7, v2, v3
	ds_read2_b32 v[2:3], v9 offset0:4 offset1:69
	s_waitcnt lgkmcnt(0)
	v_cvt_pk_bf16_f32 v8, v2, v3
	ds_read2_b32 v[2:3], v9 offset0:134 offset1:199
	s_waitcnt lgkmcnt(0)
	v_cvt_pk_bf16_f32 v9, v2, v3
	ds_read2_b32 v[2:3], v11 offset0:8 offset1:73
	s_waitcnt lgkmcnt(0)
	v_cvt_pk_bf16_f32 v10, v2, v3
	ds_read2_b32 v[2:3], v11 offset0:138 offset1:203
	s_waitcnt lgkmcnt(0)
	v_cvt_pk_bf16_f32 v11, v2, v3
	ds_read2_b32 v[2:3], v13 offset0:12 offset1:77
	s_waitcnt lgkmcnt(0)
	v_cvt_pk_bf16_f32 v12, v2, v3
	ds_read2_b32 v[2:3], v13 offset0:142 offset1:207
	s_waitcnt lgkmcnt(0)
	v_cvt_pk_bf16_f32 v13, v2, v3
	v_add_u32_e32 v2, s3, v5
	v_ashrrev_i32_e32 v3, 31, v2
	v_lshlrev_b64 v[2:3], 11, v[2:3]
	v_lshl_add_u64 v[2:3], s[18:19], 0, v[2:3]
	v_lshl_add_u64 v[2:3], v[2:3], 0, s[40:41]
	v_lshl_add_u64 v[2:3], v[2:3], 0, v[198:199]
	global_store_dwordx4 v[2:3], v[6:9], off
	global_store_dwordx4 v[2:3], v[10:13], off offset:16
	s_cbranch_execnz .LBB0_125
	s_branch .LBB0_249
